# attention DMA pieces: m0 write ahead of the address mad (no s_nop pad)
# baseline (speedup 1.0000x reference)
; #define LAS __attribute__((address_space(3)))
; __device__ __forceinline__ void attn_unit2(LAS unsigned char* lds, const bf16_t* __restrict__ Q, const bf16_t* __restrict__ KN, const bf16_t* __restrict__ KPE, ...
;     ...
;         SOFTMAX2(sa0, sa1, ma, la, oa0, oa1, pa);
;         SOFTMAX2(sb0, sb1, mb, lb, ob0, ob1, pb);
;     ...
;         const LAS unsigned char* va = lds + sc + va_off;
; #pragma unroll
;         for (int st = 0; st < 4; ++st) {
;             const bf16x8 v0 = *(const LAS bf16x8*)(va + st * 32);
;             const bf16x8 v1 = *(const LAS bf16x8*)(va + 32 * VROW + st * 32);
;             const bf16x8 fa = __builtin_bit_cast(bf16x8, pa[st]), fb = __builtin_bit_cast(bf16x8, pb[st]);
;             oa0 = __builtin_amdgcn_mfma_f32_32x32x16_bf16(v0, fa, oa0, 0, 0, 0);
;             oa1 = __builtin_amdgcn_mfma_f32_32x32x16_bf16(v1, fa, oa1, 0, 0, 0);
;             ob0 = __builtin_amdgcn_mfma_f32_32x32x16_bf16(v0, fb, ob0, 0, 0, 0);
;             ob1 = __builtin_amdgcn_mfma_f32_32x32x16_bf16(v1, fb, ob1, 0, 0, 0);
;         }
;         __builtin_amdgcn_sched_barrier(0);
;         __syncthreads();
.Lat_back_bE:
	v_add_f32_e32 v193, v193, v230
	v_cvt_pk_bf16_f32 v80, v80, v81
	v_cvt_pk_bf16_f32 v81, v82, v83
	v_mfma_f32_32x32x16_bf16 v[112:127], v[220:223], v[174:177], v[112:127]
	v_cvt_pk_bf16_f32 v82, v84, v85
	v_cvt_pk_bf16_f32 v83, v86, v87
	v_cvt_pk_bf16_f32 v84, v88, v89
	v_mfma_f32_32x32x16_bf16 v[112:127], v[240:243], v[248:251], v[112:127]
	v_cvt_pk_bf16_f32 v85, v90, v91
	v_cvt_pk_bf16_f32 v86, v92, v93
	v_cvt_pk_bf16_f32 v87, v94, v95
	s_waitcnt vmcnt(0)
	s_barrier
	s_cmp_lt_u32 s27, 2
	s_cselect_b32 s14, s10, s11
	s_add_i32 s14, s14, s24
	v_add3_u32 v224, s26, v183, v128
	ds_read_b128 v[212:215], v224 offset:0
	ds_read_b128 v[216:219], v224 offset:32
	ds_read_b128 v[220:223], v224 offset:64
	v_mfma_f32_32x32x16_bf16 v[16:31], v[196:199], v[64:67], v[16:31]
	v_exp_f32_e32 v96, v96
	v_exp_f32_e32 v97, v97
	v_exp_f32_e32 v98, v98
	v_exp_f32_e32 v99, v99
	v_mfma_f32_32x32x16_bf16 v[48:63], v[200:203], v[64:67], v[48:63]
	v_exp_f32_e32 v100, v100
	v_exp_f32_e32 v101, v101
	v_add_f32_e32 v230, v96, v97
	v_exp_f32_e32 v102, v102
	v_mfma_f32_32x32x16_bf16 v[16:31], v[204:207], v[68:71], v[16:31]
	v_exp_f32_e32 v103, v103
	v_add_f32_e32 v231, v98, v99
	v_exp_f32_e32 v104, v104
	v_exp_f32_e32 v105, v105
	v_mfma_f32_32x32x16_bf16 v[48:63], v[208:211], v[68:71], v[48:63]
	v_add_f32_e32 v230, v230, v100
	v_add_f32_e32 v231, v231, v101
	s_cmpk_gt_u32 s27, 0x81
	s_cbranch_scc1 .Lat_dmaL_0
	s_and_b64 vcc, exec, s[4:5]
	s_cbranch_vccnz .Lat_dmaL_0
	s_add_i32 m0, s25, s19
	v_mad_u64_u32 v[234:235], s[16:17], v182, s14, v[180:181]
	global_load_lds_dwordx4 v[234:235], off
.Lat_dmaL_0:
	v_exp_f32_e32 v106, v106
	v_exp_f32_e32 v107, v107
	v_add_f32_e32 v230, v230, v102
	v_add_f32_e32 v231, v231, v103
	v_mfma_f32_32x32x16_bf16 v[32:47], v[196:199], v[80:83], v[32:47]
	v_exp_f32_e32 v108, v108
	v_exp_f32_e32 v109, v109
	s_cmpk_gt_u32 s27, 0x81
	s_cbranch_scc1 .Lat_dmaL_1
	s_and_b64 vcc, exec, s[6:7]
	s_cbranch_vccnz .Lat_dmaL_1
	s_add_i32 m0, s25, s20
	v_mad_u64_u32 v[234:235], s[16:17], v186, s14, v[184:185]
	global_load_lds_dwordx4 v[234:235], off
.Lat_dmaL_1:
	v_add_f32_e32 v230, v230, v104
	v_add_f32_e32 v231, v231, v105
	v_mfma_f32_32x32x16_bf16 v[0:15], v[200:203], v[80:83], v[0:15]
	v_exp_f32_e32 v110, v110
	v_exp_f32_e32 v111, v111
	v_add_f32_e32 v230, v230, v106
	v_add_f32_e32 v231, v231, v107
	v_mfma_f32_32x32x16_bf16 v[32:47], v[204:207], v[84:87], v[32:47]
	v_add_f32_e32 v230, v230, v108
	s_cmpk_gt_u32 s27, 0x81
	s_cbranch_scc1 .Lat_dmaL_2
	s_and_b64 vcc, exec, s[8:9]
	s_cbranch_vccnz .Lat_dmaL_2
	s_add_i32 m0, s25, s21
	v_mad_u64_u32 v[234:235], s[16:17], v190, s14, v[188:189]
	global_load_lds_dwordx4 v[234:235], off
